# scan chunk loop edge: counter/exit test hoisted above the chunk barrier; scan waves branch straight to the chunk code
# speedup vs baseline: 1.0126x; 1.0041x over previous
; __device__ __forceinline__ void phase_scan(KP p) {
;     ...
;     for (int c = -1; c < NCH; ++c) {
;       if (w >= 4) {
;     ...
;       asm volatile("s_waitcnt lgkmcnt(0)" ::: "memory");
;       __builtin_amdgcn_s_barrier();
;       asm volatile("" ::: "memory");
;     }
.LBB0_755:
	s_or_b64 exec, exec, s[50:51]
	s_add_i32 s18, s18, 1
	s_xor_b64 s[68:69], s[68:69], -1
	s_cmpk_eq_i32 s18, 0x208
	s_waitcnt lgkmcnt(0)
	s_barrier
	s_cbranch_scc1 .LBB0_775
	s_cbranch_vccnz .LBB0_756
	s_mov_b64 s[50:51], 0
	s_movk_i32 s71, 0x600
	s_branch .Lscan_entry

; __device__ __forceinline__ void phase_scan(KP p) {
;     ...
;       } else if (c >= 0) {
;         const int buf = c & 1;
;         const float* fbase = feat + (buf * 32) * 320 + cs * 4;
;         const float* vb4 = vbuf + (buf * 16 + rowl) * 32;
;         const bool b3 = (cs & 8) != 0, b2 = (cs & 4) != 0;
;         float* yb = ybuf + (buf * 32 + (b3 ? 2 : 0) + (b2 ? 1 : 0)) * 16 + rowl;
;         float4 Ar, Aw, Ak, An, Ab, Br, Bw, Bk, Bn, Bb, Cr, Cw, Ck, Cn, Cb, Dr, Dw, Dk, Dn, Db;
;         float4 vcur = *(const float4*)vb4, vnext;
;         float q0 = 0.f, q1 = 0.f, q2 = 0.f, q3 = 0.f, p0 = 0.f, p1 = 0.f, p2 = 0.f, p3 = 0.f;
.Lscan_entry:
	s_and_b32 s70, s18, 1
	s_cmp_lg_u32 s18, 0
	s_cbranch_scc1 .Lscan_hot
	v_and_b32_e32 v93, 63, v135
	v_bfe_u32 v94, v93, 3, 2
	v_and_b32_e32 v95, 3, v93
	v_lshl_add_u32 v94, v94, 2, v95
	v_lshrrev_b32_e32 v95, 5, v93
	v_lshl_add_u32 v94, v94, 1, v95
	s_mov_b32 s19, 0x16000
	v_lshl_add_u32 v129, v94, 4, s19
	v_and_b32_e32 v94, 15, v93
	v_lshlrev_b32_e32 v95, 3, v95
	v_sub_u32_e32 v94, v94, v95
	v_and_b32_e32 v95, 1, v94
	v_lshlrev_b32_e32 v95, 4, v95
	v_mov_b32_e32 v93, 0x3f80
	v_lshlrev_b32_e32 v93, v95, v93
	v_lshrrev_b32_e32 v94, 1, v94
	v_cmp_eq_u32_e64 s[74:75], 0, v94
	s_nop 1
	v_cndmask_b32_e64 v124, 0, v93, s[74:75]
	v_cmp_eq_u32_e64 s[74:75], 1, v94
	s_nop 1
	v_cndmask_b32_e64 v125, 0, v93, s[74:75]
	v_cmp_eq_u32_e64 s[74:75], 2, v94
	s_nop 1
	v_cndmask_b32_e64 v126, 0, v93, s[74:75]
	v_cmp_eq_u32_e64 s[74:75], 3, v94
	s_nop 1
	v_cndmask_b32_e64 v127, 0, v93, s[74:75]
